# attention tail: fast-path register moves hoisted into the compare-to-branch wait; loop-carried alpha copy moved before the barrier
# speedup vs baseline: 1.0067x; 1.0007x over previous
; __device__ __forceinline__ void finishSM(f32x16& p0, f32x16& p1, float alpha, float& l_reg, bf16x8& pa0, bf16x8& pa1, bf16x8& pa2, bf16x8& pa3) {
; #pragma unroll
;     for (int r = 0; r < 16; ++r) p1[r] = __builtin_amdgcn_exp2f(p1[r]);
;     float ps = 0;
; #pragma unroll
;     for (int r = 0; r < 16; ++r) ps += p0[r];
; #pragma unroll
;     for (int r = 0; r < 16; ++r) ps += p1[r];
;     { auto rr = __builtin_amdgcn_permlane32_swap(__float_as_uint(ps), __float_as_uint(ps), false, false);
;       ps = __uint_as_float(rr[0]) + __uint_as_float(rr[1]); }
;     l_reg = l_reg * alpha + ps;
;     ...
;     PK4(p0, 0, pa0); PK4(p0, 8, pa1); PK4(p1, 0, pa2); PK4(p1, 8, pa3);
;     ...
; }
; __device__ __forceinline__ void qkt(f32x16& p0, f32x16& p1, const char* Kn, const bf16x8* qr, int r32, int hi) {
;     const char* Kr = Kn + KR_OFF;
;     p0 = f32x16{}; p1 = f32x16{};
;     __builtin_amdgcn_s_setprio(1);
; #pragma unroll
;     for (int d0 = 0; d0 < 8; ++d0) { const int cb = (d0 * 16 + hi * 8) * 2;
;         const bf16x8 b0 = *reinterpret_cast<const bf16x8*>(Kn + KNSWZ(r32, cb));
;         const bf16x8 b1 = *reinterpret_cast<const bf16x8*>(Kn + KNSWZ(32 + r32, cb));
;         p0 = __builtin_amdgcn_mfma_f32_32x32x16_bf16(b0, qr[d0], p0, 0, 0, 0);
;         p1 = __builtin_amdgcn_mfma_f32_32x32x16_bf16(b1, qr[d0], p1, 0, 0, 0); }
; #pragma unroll
;     for (int d0 = 0; d0 < 4; ++d0) { const int cb = (d0 * 16 + hi * 8) * 2;
;         const bf16x8 b0 = *reinterpret_cast<const bf16x8*>(Kr + KRSWZ(r32, cb));
;         const bf16x8 b1 = *reinterpret_cast<const bf16x8*>(Kr + KRSWZ(32 + r32, cb));
;         p0 = __builtin_amdgcn_mfma_f32_32x32x16_bf16(b0, qr[8 + d0], p0, 0, 0, 0);
;         p1 = __builtin_amdgcn_mfma_f32_32x32x16_bf16(b1, qr[8 + d0], p1, 0, 0, 0); }
; }
.LBB0_216:
	s_mul_i32 s0, s9, 0x6000
	s_add_i32 s14, s0, 0
	s_lshl_b32 s13, s9, 14
	s_add_i32 s16, s14, s6
	s_add_i32 s17, s7, s13
	s_add_i32 s18, s14, s8
	s_mov_b32 s13, s10
	s_mov_b32 s10, s15
	s_mul_i32 s0, s13, 0x6000
	s_add_i32 s0, s0, 0
	s_setprio 1
	v_add_u32_e32 v84, s0, v207
	ds_read_b128 v[80:83], v84
	ds_read_b128 v[84:87], v84 offset:8192
	v_add_u32_e32 v168, s0, v210
	ds_read_b128 v[196:199], v168
	ds_read_b128 v[168:171], v168 offset:8192
	v_add_u32_e32 v184, s0, v218
	s_waitcnt lgkmcnt(0)
	v_mfma_f32_32x32x16_bf16 v[96:111], v[80:83], v[156:159], 0
	v_mfma_f32_32x32x16_bf16 v[80:95], v[84:87], v[156:159], 0
	v_mfma_f32_32x32x16_bf16 v[96:111], v[196:199], v[152:155], v[96:111]
	v_mfma_f32_32x32x16_bf16 v[80:95], v[168:171], v[152:155], v[80:95]
	ds_read_b128 v[168:171], v184
	ds_read_b128 v[196:199], v184 offset:8192
	v_add_u32_e32 v184, s0, v221
	s_mov_b32 m0, s16
	s_add_u32 s100, s72, 0x26500000
	s_addc_u32 s101, s73, 0
	global_load_lds_dwordx4 v178, s[100:101]
	s_waitcnt lgkmcnt(0)
	v_mfma_f32_32x32x16_bf16 v[96:111], v[168:171], v[148:151], v[96:111]
	v_mfma_f32_32x32x16_bf16 v[80:95], v[196:199], v[148:151], v[80:95]
	ds_read_b128 v[168:171], v184
	ds_read_b128 v[196:199], v184 offset:8192
	v_add_u32_e32 v184, s0, v222
	s_waitcnt lgkmcnt(0)
	v_mfma_f32_32x32x16_bf16 v[96:111], v[168:171], v[144:147], v[96:111]
	v_mfma_f32_32x32x16_bf16 v[80:95], v[196:199], v[144:147], v[80:95]
	ds_read_b128 v[168:171], v184
	ds_read_b128 v[196:199], v184 offset:8192
	v_add_u32_e32 v184, s0, v223
	s_add_i32 m0, s16, 0x400
	s_nop 0
	global_load_lds_dwordx4 v180, s[100:101]
	s_waitcnt lgkmcnt(0)
	v_mfma_f32_32x32x16_bf16 v[96:111], v[168:171], v[140:143], v[96:111]
	v_mfma_f32_32x32x16_bf16 v[80:95], v[196:199], v[140:143], v[80:95]
	ds_read_b128 v[168:171], v184
	ds_read_b128 v[196:199], v184 offset:8192
	v_add_u32_e32 v184, s0, v224
	v_exp_f32_e32 v233, v73
	s_waitcnt lgkmcnt(0)
	v_mfma_f32_32x32x16_bf16 v[96:111], v[168:171], v[136:139], v[96:111]
	v_mfma_f32_32x32x16_bf16 v[80:95], v[196:199], v[136:139], v[80:95]
	ds_read_b128 v[168:171], v184
	ds_read_b128 v[196:199], v184 offset:8192
	v_add_u32_e32 v184, s0, v225
	s_mov_b32 m0, s17
	s_add_u32 s100, s72, 0x26500100
	s_addc_u32 s101, s73, 0
	global_load_lds_dwordx4 v176, s[100:101]
	v_exp_f32_e32 v250, v74
	s_waitcnt lgkmcnt(0)
	v_mfma_f32_32x32x16_bf16 v[96:111], v[168:171], v[132:135], v[96:111]
	v_mfma_f32_32x32x16_bf16 v[80:95], v[196:199], v[132:135], v[80:95]
	ds_read_b128 v[168:171], v184
	ds_read_b128 v[196:199], v184 offset:8192
	v_add_u32_e32 v184, s0, v226
	v_exp_f32_e32 v200, v75
	s_waitcnt lgkmcnt(0)
	v_mfma_f32_32x32x16_bf16 v[96:111], v[168:171], v[128:131], v[96:111]
	v_mfma_f32_32x32x16_bf16 v[80:95], v[196:199], v[128:131], v[80:95]
	ds_read_b128 v[168:171], v184 offset:16384
	ds_read_b128 v[196:199], v184 offset:20480
	v_add_u32_e32 v184, s0, v227
	s_add_i32 m0, s17, 0x400
	s_add_u32 s100, s72, 0x26500180
	s_addc_u32 s101, s73, 0
	global_load_lds_dwordx4 v176, s[100:101]
	v_exp_f32_e32 v195, v76
	s_waitcnt lgkmcnt(0)
	v_mfma_f32_32x32x16_bf16 v[96:111], v[168:171], v[124:127], v[96:111]
	v_mfma_f32_32x32x16_bf16 v[80:95], v[196:199], v[124:127], v[80:95]
	ds_read_b128 v[168:171], v184 offset:16384
	ds_read_b128 v[196:199], v184 offset:20480
	v_add_u32_e32 v184, s0, v228
	v_exp_f32_e32 v172, v77
	s_waitcnt lgkmcnt(0)
	v_mfma_f32_32x32x16_bf16 v[96:111], v[168:171], v[120:123], v[96:111]
	v_mfma_f32_32x32x16_bf16 v[80:95], v[196:199], v[120:123], v[80:95]
	ds_read_b128 v[168:171], v184 offset:16384
	ds_read_b128 v[196:199], v184 offset:20480
	v_add_u32_e32 v184, s0, v229
	s_add_i32 m0, s18, 0x4000
	s_add_u32 s100, s72, 0x21204000
	s_addc_u32 s101, s73, 0
	global_load_lds_dwordx4 v174, s[100:101]
	v_exp_f32_e32 v173, v78
	s_waitcnt lgkmcnt(0)
	v_mfma_f32_32x32x16_bf16 v[96:111], v[168:171], v[116:119], v[96:111]
	v_mfma_f32_32x32x16_bf16 v[80:95], v[196:199], v[116:119], v[80:95]
	ds_read_b128 v[168:171], v184 offset:16384
	ds_read_b128 v[196:199], v184 offset:20480
	v_exp_f32_e32 v184, v68
	v_exp_f32_e32 v79, v79
	s_waitcnt lgkmcnt(0)
	v_mfma_f32_32x32x16_bf16 v[96:111], v[168:171], v[112:115], v[96:111]
	v_exp_f32_e32 v168, v64
	v_add_f32_e32 v64, 0, v247
	v_add_f32_e32 v64, v249, v64
	v_add_f32_e32 v64, v245, v64
	v_add_f32_e32 v64, v248, v64
	v_add_f32_e32 v64, v244, v64
	v_add_f32_e32 v64, v246, v64
	v_add_f32_e32 v64, v242, v64
	v_add_f32_e32 v64, v243, v64
	v_add_f32_e32 v64, v239, v64
	v_add_f32_e32 v64, v241, v64
	v_add_f32_e32 v64, v238, v64
	v_add_f32_e32 v64, v240, v64
	v_add_f32_e32 v64, v235, v64
	v_exp_f32_e32 v169, v65
	v_add_f32_e32 v64, v237, v64
	v_exp_f32_e32 v170, v66
	v_add_f32_e32 v64, v234, v64
	v_exp_f32_e32 v171, v67
	v_add_f32_e32 v64, v236, v64
	v_add_f32_e32 v64, v168, v64
	v_mfma_f32_32x32x16_bf16 v[80:95], v[196:199], v[112:115], v[80:95]
	v_exp_f32_e32 v196, v69
	v_add_f32_e32 v64, v169, v64
	v_exp_f32_e32 v197, v70
	v_add_f32_e32 v64, v170, v64
	v_exp_f32_e32 v198, v71
	v_add_f32_e32 v64, v171, v64
	v_exp_f32_e32 v199, v72
	v_add_f32_e32 v64, v184, v64
	v_add_f32_e32 v64, v196, v64
	v_add_f32_e32 v64, v197, v64
	v_add_f32_e32 v64, v198, v64
	v_add_f32_e32 v64, v199, v64
	v_add_f32_e32 v64, v233, v64
	v_add_f32_e32 v64, v250, v64
	v_add_f32_e32 v64, v200, v64
	v_add_f32_e32 v64, v195, v64
	v_add_f32_e32 v64, v172, v64
	v_add_f32_e32 v64, v173, v64
	v_add_f32_e32 v231, v79, v64
	v_mov_b32_e32 v232, v231
	v_cvt_pk_bf16_f32 v64, v247, v249
	v_cvt_pk_bf16_f32 v65, v245, v248
	v_cvt_pk_bf16_f32 v66, v244, v246
	s_nop 1
	v_permlane32_swap_b32_e32 v231, v232
	v_cvt_pk_bf16_f32 v67, v242, v243
	v_permlane32_swap_b32_e32 v64, v66
	v_cvt_pk_bf16_f32 v68, v239, v241
	v_cvt_pk_bf16_f32 v69, v238, v240
	v_cvt_pk_bf16_f32 v70, v235, v237
	v_cvt_pk_bf16_f32 v71, v234, v236
	v_cvt_pk_bf16_f32 v72, v168, v169
	v_cvt_pk_bf16_f32 v73, v170, v171
	v_cvt_pk_bf16_f32 v74, v184, v196
	v_cvt_pk_bf16_f32 v75, v197, v198
	v_cvt_pk_bf16_f32 v76, v199, v233
	v_cvt_pk_bf16_f32 v77, v250, v200
	v_cvt_pk_bf16_f32 v78, v195, v172
	v_cvt_pk_bf16_f32 v79, v173, v79
	v_permlane32_swap_b32_e32 v65, v67
	v_permlane32_swap_b32_e32 v68, v70
	v_permlane32_swap_b32_e32 v69, v71
	v_permlane32_swap_b32_e32 v72, v74
	v_permlane32_swap_b32_e32 v73, v75
	v_permlane32_swap_b32_e32 v76, v78
	v_permlane32_swap_b32_e32 v77, v79
	s_setprio 0
	s_lshl_b32 s15, s15, 14
	v_add_u32_e32 v172, s15, v205
	ds_read_b64_tr_b16 v[168:169], v172 offset:0
	ds_read_b64_tr_b16 v[170:171], v172 offset:0x800
	ds_read_b64_tr_b16 v[196:197], v172 offset:0x1000
	ds_read_b64_tr_b16 v[198:199], v172 offset:0x1800
	ds_read_b64_tr_b16 v[234:235], v172 offset:0x2000
	ds_read_b64_tr_b16 v[236:237], v172 offset:0x2800
	ds_read_b64_tr_b16 v[238:239], v172 offset:0x3000
	ds_read_b64_tr_b16 v[240:241], v172 offset:0x3800
	s_waitcnt lgkmcnt(0)
; template <bool FIRST>
; __device__ __forceinline__ void partialSM(f32x16& p0, f32x16& p1, float& m_reg, float& mn, float& alpha) {
;     ...
;     else if (__builtin_expect(__all(pmax - m_reg <= THRL), 1)) { mn = m_reg; alpha = 1.f; }
;     else { mn = fmaxf(m_reg, pmax); alpha = __builtin_amdgcn_exp2f(m_reg - mn); m_reg = mn; }
;     if (!__builtin_expect(__all(mn == 0.f), 1)) {
	s_nop 0
	v_mfma_f32_32x32x16_bf16 v[0:15], v[64:67], v[168:171], v[0:15]
	ds_read_b64_tr_b16 v[168:169], v172 offset:0x200
	ds_read_b64_tr_b16 v[170:171], v172 offset:0xa00
	v_mfma_f32_32x32x16_bf16 v[0:15], v[68:71], v[196:199], v[0:15]
	ds_read_b64_tr_b16 v[196:197], v172 offset:0x1200
	ds_read_b64_tr_b16 v[198:199], v172 offset:0x1a00
	v_mfma_f32_32x32x16_bf16 v[0:15], v[72:75], v[234:237], v[0:15]
	ds_read_b64_tr_b16 v[234:235], v172 offset:0x2200
	ds_read_b64_tr_b16 v[236:237], v172 offset:0x2a00
	v_mfma_f32_32x32x16_bf16 v[0:15], v[76:79], v[238:241], v[0:15]
	ds_read_b64_tr_b16 v[238:239], v172 offset:0x3200
	ds_read_b64_tr_b16 v[240:241], v172 offset:0x3a00
	s_waitcnt lgkmcnt(0)
	v_mfma_f32_32x32x16_bf16 v[48:63], v[64:67], v[168:171], v[48:63]
	ds_read_b64_tr_b16 v[168:169], v172 offset:0x400
	ds_read_b64_tr_b16 v[170:171], v172 offset:0xc00
	v_mfma_f32_32x32x16_bf16 v[48:63], v[68:71], v[196:199], v[48:63]
	ds_read_b64_tr_b16 v[196:197], v172 offset:0x1400
	ds_read_b64_tr_b16 v[198:199], v172 offset:0x1c00
	v_mfma_f32_32x32x16_bf16 v[48:63], v[72:75], v[234:237], v[48:63]
	ds_read_b64_tr_b16 v[234:235], v172 offset:0x2400
	ds_read_b64_tr_b16 v[236:237], v172 offset:0x2c00
	v_mfma_f32_32x32x16_bf16 v[48:63], v[76:79], v[238:241], v[48:63]
	ds_read_b64_tr_b16 v[238:239], v172 offset:0x3400
	ds_read_b64_tr_b16 v[240:241], v172 offset:0x3c00
	s_waitcnt lgkmcnt(0)
	v_mfma_f32_32x32x16_bf16 v[32:47], v[64:67], v[168:171], v[32:47]
	ds_read_b64_tr_b16 v[168:169], v172 offset:0x600
	ds_read_b64_tr_b16 v[170:171], v172 offset:0xe00
	v_mfma_f32_32x32x16_bf16 v[32:47], v[68:71], v[196:199], v[32:47]
	ds_read_b64_tr_b16 v[196:197], v172 offset:0x1600
	ds_read_b64_tr_b16 v[198:199], v172 offset:0x1e00
	v_mfma_f32_32x32x16_bf16 v[32:47], v[72:75], v[234:237], v[32:47]
	ds_read_b64_tr_b16 v[234:235], v172 offset:0x2600
	ds_read_b64_tr_b16 v[236:237], v172 offset:0x2e00
	v_mfma_f32_32x32x16_bf16 v[32:47], v[76:79], v[238:241], v[32:47]
	ds_read_b64_tr_b16 v[238:239], v172 offset:0x3600
	ds_read_b64_tr_b16 v[240:241], v172 offset:0x3e00
	s_waitcnt lgkmcnt(0)
	v_mfma_f32_32x32x16_bf16 v[16:31], v[64:67], v[168:171], v[16:31]
	v_max_f32_e32 v64, v97, v97
	v_max_f32_e32 v65, v96, v96
	v_max_f32_e32 v64, v65, v64
	v_max3_f32 v64, v64, v98, v99
	v_max3_f32 v64, v64, v100, v101
	v_max3_f32 v64, v64, v102, v103
	v_max3_f32 v64, v64, v104, v105
	v_mfma_f32_32x32x16_bf16 v[16:31], v[68:71], v[196:199], v[16:31]
	v_max3_f32 v64, v64, v106, v107
	v_max3_f32 v64, v64, v108, v109
	v_max3_f32 v64, v64, v110, v111
	v_max3_f32 v64, v64, v80, v81
	v_max3_f32 v64, v64, v82, v83
	v_max3_f32 v64, v64, v84, v85
	v_max3_f32 v64, v64, v86, v87
	v_mfma_f32_32x32x16_bf16 v[16:31], v[72:75], v[234:237], v[16:31]
	v_max3_f32 v64, v64, v88, v89
	v_max3_f32 v64, v64, v90, v91
	v_max3_f32 v64, v64, v92, v93
	v_max3_f32 v64, v64, v94, v95
	v_mov_b32_e32 v65, v64
	s_nop 1
	v_permlane32_swap_b32_e32 v64, v65
	v_max_f32_e32 v65, v65, v65
	v_max_f32_e32 v64, v64, v64
	v_mfma_f32_32x32x16_bf16 v[16:31], v[76:79], v[238:241], v[16:31]
	v_max_f32_e32 v64, v64, v65
	v_sub_f32_e32 v65, v64, v182
	s_mov_b32 s0, 0x41300000
	v_cmp_ge_f32_e32 vcc, s0, v65
	v_mov_b32_e32 v184, v182
	v_mov_b32_e32 v233, 1.0
	s_cmp_eq_u64 vcc, exec
	s_cbranch_scc0 .Latt_slow1
	s_cmp_lg_u32 s19, 0
	s_cbranch_scc0 .LBB0_228
.LBB0_221:
	v_exp_f32_e32 v182, v98
	v_exp_f32_e32 v172, v96
	v_exp_f32_e32 v173, v97
	v_exp_f32_e32 v195, v99
	v_exp_f32_e32 v196, v100
	v_exp_f32_e32 v197, v101
	v_exp_f32_e32 v198, v102
	v_exp_f32_e32 v199, v103
	v_exp_f32_e32 v200, v104
	v_exp_f32_e32 v234, v105
	v_exp_f32_e32 v235, v106
	v_exp_f32_e32 v236, v107
	v_exp_f32_e32 v237, v108
	v_exp_f32_e32 v238, v109
	v_exp_f32_e32 v239, v110
	v_exp_f32_e32 v240, v111
	s_mul_i32 s0, s10, 0x6000
	s_add_i32 s16, s0, 0
	s_add_i32 s17, s16, s6
	s_add_i32 s18, s16, s8
	s_waitcnt vmcnt(0) lgkmcnt(0)
	s_barrier
	s_add_i32 s15, s7, s15
	s_setprio 1
	v_add_u32_e32 v68, s14, v207
	ds_read_b128 v[64:67], v68
	ds_read_b128 v[68:71], v68 offset:8192
	v_add_u32_e32 v186, s14, v210
	ds_read_b128 v[168:171], v186
	ds_read_b128 v[186:189], v186 offset:8192
	s_waitcnt lgkmcnt(0)
	v_mfma_f32_32x32x16_bf16 v[96:111], v[64:67], v[156:159], 0
	v_mfma_f32_32x32x16_bf16 v[64:79], v[68:71], v[156:159], 0
	v_mfma_f32_32x32x16_bf16 v[96:111], v[168:171], v[152:155], v[96:111]
	v_mfma_f32_32x32x16_bf16 v[64:79], v[186:189], v[152:155], v[64:79]
	v_add_u32_e32 v186, s14, v218
	ds_read_b128 v[168:171], v186
	ds_read_b128 v[186:189], v186 offset:8192
	s_mov_b32 m0, s17
	s_add_u32 s100, s72, 0x26580000
	s_addc_u32 s101, s73, 0
	global_load_lds_dwordx4 v178, s[100:101]
	s_waitcnt lgkmcnt(0)
	v_mfma_f32_32x32x16_bf16 v[96:111], v[168:171], v[148:151], v[96:111]
	v_mfma_f32_32x32x16_bf16 v[64:79], v[186:189], v[148:151], v[64:79]
	v_add_u32_e32 v186, s14, v221
	ds_read_b128 v[168:171], v186
	ds_read_b128 v[186:189], v186 offset:8192
	s_waitcnt lgkmcnt(0)
	v_mfma_f32_32x32x16_bf16 v[96:111], v[168:171], v[144:147], v[96:111]
	v_mfma_f32_32x32x16_bf16 v[64:79], v[186:189], v[144:147], v[64:79]
	v_add_u32_e32 v186, s14, v222
	ds_read_b128 v[168:171], v186
	ds_read_b128 v[186:189], v186 offset:8192
	s_add_i32 m0, s17, 0x400
	s_nop 0
	global_load_lds_dwordx4 v180, s[100:101]
	v_exp_f32_e32 v190, v88
	s_waitcnt lgkmcnt(0)
	v_mfma_f32_32x32x16_bf16 v[96:111], v[168:171], v[140:143], v[96:111]
	v_mfma_f32_32x32x16_bf16 v[64:79], v[186:189], v[140:143], v[64:79]
	v_add_u32_e32 v186, s14, v223
	ds_read_b128 v[168:171], v186
	ds_read_b128 v[186:189], v186 offset:8192
	v_exp_f32_e32 v191, v89
	s_waitcnt lgkmcnt(0)
; __device__ __forceinline__ void finishSM(f32x16& p0, f32x16& p1, float alpha, float& l_reg, bf16x8& pa0, bf16x8& pa1, bf16x8& pa2, bf16x8& pa3) {
; #pragma unroll
;     for (int r = 0; r < 16; ++r) p1[r] = __builtin_amdgcn_exp2f(p1[r]);
;     float ps = 0;
; #pragma unroll
;     for (int r = 0; r < 16; ++r) ps += p0[r];
; #pragma unroll
;     for (int r = 0; r < 16; ++r) ps += p1[r];
;     { auto rr = __builtin_amdgcn_permlane32_swap(__float_as_uint(ps), __float_as_uint(ps), false, false);
;       ps = __uint_as_float(rr[0]) + __uint_as_float(rr[1]); }
;     l_reg = l_reg * alpha + ps;
;     ...
;     PK4(p0, 0, pa0); PK4(p0, 8, pa1); PK4(p1, 0, pa2); PK4(p1, 8, pa3);
;     ...
; }
; __device__ __forceinline__ void qkt(f32x16& p0, f32x16& p1, const char* Kn, const bf16x8* qr, int r32, int hi) {
;     const char* Kr = Kn + KR_OFF;
;     p0 = f32x16{}; p1 = f32x16{};
;     __builtin_amdgcn_s_setprio(1);
; #pragma unroll
;     for (int d0 = 0; d0 < 8; ++d0) { const int cb = (d0 * 16 + hi * 8) * 2;
;         const bf16x8 b0 = *reinterpret_cast<const bf16x8*>(Kn + KNSWZ(r32, cb));
;         const bf16x8 b1 = *reinterpret_cast<const bf16x8*>(Kn + KNSWZ(32 + r32, cb));
;         p0 = __builtin_amdgcn_mfma_f32_32x32x16_bf16(b0, qr[d0], p0, 0, 0, 0);
;         p1 = __builtin_amdgcn_mfma_f32_32x32x16_bf16(b1, qr[d0], p1, 0, 0, 0); }
; #pragma unroll
;     for (int d0 = 0; d0 < 4; ++d0) { const int cb = (d0 * 16 + hi * 8) * 2;
;         const bf16x8 b0 = *reinterpret_cast<const bf16x8*>(Kr + KRSWZ(r32, cb));
;         const bf16x8 b1 = *reinterpret_cast<const bf16x8*>(Kr + KRSWZ(32 + r32, cb));
;         p0 = __builtin_amdgcn_mfma_f32_32x32x16_bf16(b0, qr[8 + d0], p0, 0, 0, 0);
;         p1 = __builtin_amdgcn_mfma_f32_32x32x16_bf16(b1, qr[8 + d0], p1, 0, 0, 0); }
; }
	v_mfma_f32_32x32x16_bf16 v[96:111], v[168:171], v[136:139], v[96:111]
	v_mfma_f32_32x32x16_bf16 v[64:79], v[186:189], v[136:139], v[64:79]
	v_add_u32_e32 v186, s14, v224
	ds_read_b128 v[168:171], v186
	ds_read_b128 v[186:189], v186 offset:8192
	s_mov_b32 m0, s15
	s_add_u32 s100, s72, 0x26580100
	s_addc_u32 s101, s73, 0
	global_load_lds_dwordx4 v176, s[100:101]
	v_exp_f32_e32 v192, v90
	s_waitcnt lgkmcnt(0)
	v_mfma_f32_32x32x16_bf16 v[96:111], v[168:171], v[132:135], v[96:111]
	v_mfma_f32_32x32x16_bf16 v[64:79], v[186:189], v[132:135], v[64:79]
	v_add_u32_e32 v186, s14, v225
	ds_read_b128 v[168:171], v186
	ds_read_b128 v[186:189], v186 offset:8192
	v_exp_f32_e32 v193, v91
	s_waitcnt lgkmcnt(0)
	v_mfma_f32_32x32x16_bf16 v[96:111], v[168:171], v[128:131], v[96:111]
	v_mfma_f32_32x32x16_bf16 v[64:79], v[186:189], v[128:131], v[64:79]
	v_add_u32_e32 v186, s14, v226
	ds_read_b128 v[168:171], v186 offset:16384
	ds_read_b128 v[186:189], v186 offset:20480
	s_add_i32 m0, s15, 0x400
	s_add_u32 s100, s72, 0x26580180
	s_addc_u32 s101, s73, 0
	global_load_lds_dwordx4 v176, s[100:101]
	v_exp_f32_e32 v241, v92
	s_waitcnt lgkmcnt(0)
	v_mfma_f32_32x32x16_bf16 v[96:111], v[168:171], v[124:127], v[96:111]
	v_mfma_f32_32x32x16_bf16 v[64:79], v[186:189], v[124:127], v[64:79]
	v_add_u32_e32 v186, s14, v227
	ds_read_b128 v[168:171], v186 offset:16384
	ds_read_b128 v[186:189], v186 offset:20480
	v_exp_f32_e32 v242, v93
	s_waitcnt lgkmcnt(0)
	v_mfma_f32_32x32x16_bf16 v[96:111], v[168:171], v[120:123], v[96:111]
	v_mfma_f32_32x32x16_bf16 v[64:79], v[186:189], v[120:123], v[64:79]
	v_add_u32_e32 v186, s14, v228
	ds_read_b128 v[168:171], v186 offset:16384
	ds_read_b128 v[186:189], v186 offset:20480
	s_add_i32 m0, s18, 0x4000
	s_add_u32 s100, s72, 0x21206000
	s_addc_u32 s101, s73, 0
	global_load_lds_dwordx4 v174, s[100:101]
	v_exp_f32_e32 v94, v94
	s_waitcnt lgkmcnt(0)
	v_mfma_f32_32x32x16_bf16 v[96:111], v[168:171], v[116:119], v[96:111]
	v_mfma_f32_32x32x16_bf16 v[64:79], v[186:189], v[116:119], v[64:79]
	v_add_u32_e32 v186, s14, v229
	ds_read_b128 v[168:171], v186 offset:16384
	ds_read_b128 v[186:189], v186 offset:20480
	v_exp_f32_e32 v95, v95
	s_waitcnt lgkmcnt(0)
	v_mfma_f32_32x32x16_bf16 v[96:111], v[168:171], v[112:115], v[96:111]
	v_exp_f32_e32 v168, v80
	v_add_f32_e32 v80, 0, v172
	v_add_f32_e32 v80, v173, v80
	v_add_f32_e32 v80, v182, v80
	v_add_f32_e32 v80, v195, v80
	v_add_f32_e32 v80, v196, v80
	v_add_f32_e32 v80, v197, v80
	v_add_f32_e32 v80, v198, v80
	v_add_f32_e32 v80, v199, v80
	v_add_f32_e32 v80, v200, v80
	v_add_f32_e32 v80, v234, v80
	v_add_f32_e32 v80, v235, v80
	v_add_f32_e32 v80, v236, v80
	v_add_f32_e32 v80, v237, v80
	v_exp_f32_e32 v169, v81
	v_add_f32_e32 v80, v238, v80
	v_exp_f32_e32 v170, v82
	v_add_f32_e32 v80, v239, v80
	v_exp_f32_e32 v171, v83
	v_add_f32_e32 v80, v240, v80
	v_mfma_f32_32x32x16_bf16 v[64:79], v[186:189], v[112:115], v[64:79]
	v_exp_f32_e32 v186, v84
	v_add_f32_e32 v80, v168, v80
	v_exp_f32_e32 v187, v85
	v_add_f32_e32 v80, v169, v80
	v_exp_f32_e32 v188, v86
	v_add_f32_e32 v80, v170, v80
	v_exp_f32_e32 v189, v87
	v_add_f32_e32 v80, v171, v80
	v_add_f32_e32 v80, v186, v80
	v_add_f32_e32 v80, v187, v80
	v_add_f32_e32 v80, v188, v80
	v_add_f32_e32 v80, v189, v80
	v_add_f32_e32 v80, v190, v80
	v_add_f32_e32 v80, v191, v80
	v_add_f32_e32 v80, v192, v80
	v_add_f32_e32 v80, v193, v80
	v_add_f32_e32 v80, v241, v80
	v_add_f32_e32 v80, v242, v80
	v_add_f32_e32 v80, v94, v80
	v_add_f32_e32 v80, v95, v80
	v_mov_b32_e32 v81, v80
	v_cvt_pk_bf16_f32 v82, v172, v173
	v_cvt_pk_bf16_f32 v83, v182, v195
	v_cvt_pk_bf16_f32 v84, v196, v197
	s_nop 1
	v_permlane32_swap_b32_e32 v80, v81
	v_cvt_pk_bf16_f32 v85, v198, v199
	v_permlane32_swap_b32_e32 v82, v84
	v_cvt_pk_bf16_f32 v86, v200, v234
	v_cvt_pk_bf16_f32 v87, v235, v236
	v_cvt_pk_bf16_f32 v88, v237, v238
	v_cvt_pk_bf16_f32 v89, v239, v240
	v_cvt_pk_bf16_f32 v90, v168, v169
	v_cvt_pk_bf16_f32 v91, v170, v171
	v_cvt_pk_bf16_f32 v92, v186, v187
	v_cvt_pk_bf16_f32 v93, v188, v189
	v_cvt_pk_bf16_f32 v168, v190, v191
	v_cvt_pk_bf16_f32 v169, v192, v193
	v_cvt_pk_bf16_f32 v170, v241, v242
	v_cvt_pk_bf16_f32 v171, v94, v95
	v_permlane32_swap_b32_e32 v83, v85
	v_permlane32_swap_b32_e32 v86, v88
	v_permlane32_swap_b32_e32 v87, v89
	v_permlane32_swap_b32_e32 v90, v92
	v_permlane32_swap_b32_e32 v91, v93
	v_permlane32_swap_b32_e32 v168, v170
	v_permlane32_swap_b32_e32 v169, v171
	s_setprio 0
	v_lshl_add_u32 v94, s13, 14, v205
	ds_read_b64_tr_b16 v[186:187], v94 offset:0
	ds_read_b64_tr_b16 v[188:189], v94 offset:0x800
	ds_read_b64_tr_b16 v[190:191], v94 offset:0x1000
	ds_read_b64_tr_b16 v[192:193], v94 offset:0x1800
	ds_read_b64_tr_b16 v[196:197], v94 offset:0x2000
	ds_read_b64_tr_b16 v[198:199], v94 offset:0x2800
	ds_read_b64_tr_b16 v[234:235], v94 offset:0x3000
	ds_read_b64_tr_b16 v[236:237], v94 offset:0x3800
	s_waitcnt lgkmcnt(0)
; #define SBAR() __builtin_amdgcn_sched_barrier(0)
; #define WAIT_BAR() asm volatile("s_waitcnt vmcnt(0) lgkmcnt(0)\n\ts_barrier" ::: "memory")
; #define RESC(a) do { if (__any((a) < 1.f)) { if (hi == 0) al_l[r32] = (a); asm volatile("s_waitcnt lgkmcnt(0)" ::: "memory"); \
;     _Pragma("unroll") for (int d = 0; d < 4; ++d) _Pragma("unroll") for (int r = 0; r < 16; ++r) o[d][r] *= al_l[crow(r, hi)]; } } while (0)
; #define ROT() do { const int t_ = s_prev; s_prev = s_cur; s_cur = s_next; s_next = t_; } while (0)
; __device__ __forceinline__ void finishSM(f32x16& p0, f32x16& p1, float alpha, float& l_reg, bf16x8& pa0, bf16x8& pa1, bf16x8& pa2, bf16x8& pa3) {
;     ...
;     l_reg = l_reg * alpha + ps;
; __device__ __forceinline__ void attn_unit(const bf16_t* __restrict__ Qb, const bf16_t* __restrict__ Kn, const bf16_t* __restrict__ Vh, const bf16_t* __restrict__ Kr,
;                                           bf16_t* __restrict__ Ob, int seq, char* lds, int wv_) { LAUNDER_IDS;
;     ...
;         finishSM(pB0, pB1, alB, l_reg, pa0, pa1, pa2, pa3); __builtin_amdgcn_s_setprio(0); SBAR();
;         pv_d0(o, vb0 + s_prev * SLOT_V, pa0, pa1, pa2, pa3); partialSM<false>(pA0, pA1, m_reg, mnA, alA);
;         RESC(alA); WAIT_BAR(); ROT();
	s_nop 0
	v_mfma_f32_32x32x16_bf16 v[0:15], v[82:85], v[186:189], v[0:15]
	ds_read_b64_tr_b16 v[186:187], v94 offset:0x200
	ds_read_b64_tr_b16 v[188:189], v94 offset:0xa00
	v_mfma_f32_32x32x16_bf16 v[0:15], v[86:89], v[190:193], v[0:15]
	ds_read_b64_tr_b16 v[190:191], v94 offset:0x1200
	ds_read_b64_tr_b16 v[192:193], v94 offset:0x1a00
	v_mfma_f32_32x32x16_bf16 v[0:15], v[90:93], v[196:199], v[0:15]
	ds_read_b64_tr_b16 v[196:197], v94 offset:0x2200
	ds_read_b64_tr_b16 v[198:199], v94 offset:0x2a00
	v_mfma_f32_32x32x16_bf16 v[0:15], v[168:171], v[234:237], v[0:15]
	ds_read_b64_tr_b16 v[234:235], v94 offset:0x3200
	ds_read_b64_tr_b16 v[236:237], v94 offset:0x3a00
	s_waitcnt lgkmcnt(0)
	v_mfma_f32_32x32x16_bf16 v[48:63], v[82:85], v[186:189], v[48:63]
	ds_read_b64_tr_b16 v[186:187], v94 offset:0x400
	ds_read_b64_tr_b16 v[188:189], v94 offset:0xc00
	v_mfma_f32_32x32x16_bf16 v[48:63], v[86:89], v[190:193], v[48:63]
	ds_read_b64_tr_b16 v[190:191], v94 offset:0x1400
	ds_read_b64_tr_b16 v[192:193], v94 offset:0x1c00
	v_mfma_f32_32x32x16_bf16 v[48:63], v[90:93], v[196:199], v[48:63]
	ds_read_b64_tr_b16 v[196:197], v94 offset:0x2400
	ds_read_b64_tr_b16 v[198:199], v94 offset:0x2c00
	v_mfma_f32_32x32x16_bf16 v[48:63], v[168:171], v[234:237], v[48:63]
	ds_read_b64_tr_b16 v[234:235], v94 offset:0x3400
	ds_read_b64_tr_b16 v[236:237], v94 offset:0x3c00
	s_waitcnt lgkmcnt(0)
	v_mfma_f32_32x32x16_bf16 v[32:47], v[82:85], v[186:189], v[32:47]
	ds_read_b64_tr_b16 v[186:187], v94 offset:0x600
	ds_read_b64_tr_b16 v[188:189], v94 offset:0xe00
	v_mfma_f32_32x32x16_bf16 v[32:47], v[86:89], v[190:193], v[32:47]
	ds_read_b64_tr_b16 v[190:191], v94 offset:0x1600
	ds_read_b64_tr_b16 v[192:193], v94 offset:0x1e00
	v_mfma_f32_32x32x16_bf16 v[32:47], v[90:93], v[196:199], v[32:47]
	ds_read_b64_tr_b16 v[196:197], v94 offset:0x2600
	ds_read_b64_tr_b16 v[198:199], v94 offset:0x2e00
	v_mfma_f32_32x32x16_bf16 v[32:47], v[168:171], v[234:237], v[32:47]
	ds_read_b64_tr_b16 v[234:235], v94 offset:0x3600
	ds_read_b64_tr_b16 v[236:237], v94 offset:0x3e00
	s_waitcnt lgkmcnt(0)
	v_mfma_f32_32x32x16_bf16 v[16:31], v[82:85], v[186:189], v[16:31]
	v_max_f32_e32 v82, v97, v97
	v_max_f32_e32 v83, v96, v96
	v_max_f32_e32 v82, v83, v82
	v_max3_f32 v82, v82, v98, v99
	v_max3_f32 v82, v82, v100, v101
	v_max3_f32 v82, v82, v102, v103
	v_max3_f32 v82, v82, v104, v105
	v_mfma_f32_32x32x16_bf16 v[16:31], v[86:89], v[190:193], v[16:31]
	v_max3_f32 v82, v82, v106, v107
	v_max3_f32 v82, v82, v108, v109
	v_max3_f32 v82, v82, v110, v111
	v_max3_f32 v82, v82, v64, v65
	v_max3_f32 v82, v82, v66, v67
	v_max3_f32 v82, v82, v68, v69
	v_max3_f32 v82, v82, v70, v71
	v_mfma_f32_32x32x16_bf16 v[16:31], v[90:93], v[196:199], v[16:31]
	v_max3_f32 v82, v82, v72, v73
	v_max3_f32 v82, v82, v74, v75
	v_max3_f32 v82, v82, v76, v77
	v_max3_f32 v82, v82, v78, v79
	v_mov_b32_e32 v83, v82
	s_nop 1
	v_permlane32_swap_b32_e32 v82, v83
	v_max_f32_e32 v83, v83, v83
	v_max_f32_e32 v82, v82, v82
	v_mfma_f32_32x32x16_bf16 v[16:31], v[168:171], v[234:237], v[16:31]
	v_max_f32_e32 v82, v82, v83
	v_sub_f32_e32 v83, v82, v184
	s_mov_b32 s0, 0x41300000
	v_cmp_ge_f32_e32 vcc, s0, v83
	v_mov_b32_e32 v182, v184
	s_cmp_eq_u64 vcc, exec
	s_cbranch_scc0 .Latt_slow2
	s_cmp_lg_u32 s19, 0
	s_cbranch_scc0 .LBB0_229
	v_mov_b32_e32 v184, 1.0
.LBB0_226:
	v_exp_f32_e32 v247, v96
	v_exp_f32_e32 v249, v97
	v_exp_f32_e32 v245, v98
	v_exp_f32_e32 v248, v99
	v_exp_f32_e32 v244, v100
	v_exp_f32_e32 v246, v101
	v_exp_f32_e32 v242, v102
	v_exp_f32_e32 v243, v103
	v_exp_f32_e32 v239, v104
	v_exp_f32_e32 v241, v105
	v_exp_f32_e32 v238, v106
	v_exp_f32_e32 v240, v107
	v_exp_f32_e32 v235, v108
	v_exp_f32_e32 v237, v109
	v_exp_f32_e32 v234, v110
	v_exp_f32_e32 v236, v111
	v_add_f32_e32 v82, v231, v232
	s_mov_b64 s[0:1], 0x4000
	v_fmac_f32_e32 v82, v230, v203
	v_add_f32_e32 v203, v80, v81
	s_add_i32 s11, s11, 2
	v_lshl_add_u64 v[174:175], v[174:175], 0, s[0:1]
	s_mov_b64 s[0:1], 0x100000
	v_fmac_f32_e32 v203, v82, v233
	v_lshl_add_u64 v[176:177], v[176:177], 0, s[0:1]
	v_lshl_add_u64 v[178:179], v[178:179], 0, s[0:1]
	v_lshl_add_u64 v[180:181], v[180:181], 0, s[0:1]
	v_mov_b32_e32 v230, v184
	s_waitcnt vmcnt(0) lgkmcnt(0)
	s_barrier
	s_cmpk_gt_u32 s11, 0x7c
	s_cbranch_scc1 .LBB0_230
	s_mov_b32 s15, s9
	s_mov_b32 s9, s13
	s_branch .LBB0_216
